# stack: loop-edge hoist + split-phase P5->P6 barrier around the PLE GEMM + P1 row statistics loaded one unit ahead (on top of v59)
# speedup vs baseline: 1.0054x; 1.0006x over previous
.LBB0_161:
	s_mov_b64 s[18:19], 0x80
	s_add_i32 m0, s39, 0x18000
	v_lshl_add_u64 v[6:7], v[6:7], 0, s[18:19]
	s_waitcnt vmcnt(2)
	s_barrier
	global_load_lds_dwordx4 v[6:7], off
	v_lshl_add_u64 v[4:5], v[4:5], 0, s[18:19]
	s_add_i32 m0, s39, 0x1a000
	s_add_i32 s44, s39, 0x8000
	s_add_i32 s45, s39, 0xa000
	global_load_lds_dwordx4 v[4:5], off
	v_lshl_add_u64 v[0:1], v[0:1], 0, s[18:19]
	s_mov_b32 m0, s44
	s_add_u32 s20, s34, 0x80080
	global_load_lds_dwordx4 v[0:1], off
	v_lshl_add_u64 v[0:1], v[2:3], 0, s[18:19]
	s_mov_b32 m0, s45
	s_addc_u32 s21, s35, 0
	global_load_lds_dwordx4 v[0:1], off
	s_add_i32 m0, s39, 0x1c000
	v_lshl_add_u64 v[0:1], s[20:21], 0, v[132:133]
	global_load_lds_dwordx4 v[0:1], off
	v_lshl_add_u64 v[0:1], s[20:21], 0, v[128:129]
	s_add_i32 m0, s39, 0x1e000
	s_sext_i32_i16 s9, s6
	global_load_lds_dwordx4 v[0:1], off
	v_and_b32_e32 v0, 15, v8
	v_or_b32_e32 v148, s87, v0
	v_lshlrev_b32_e32 v3, 6, v148
	v_and_b32_e32 v4, 48, v8
	s_movk_i32 s6, 0x3c0
	v_ashrrev_i32_e32 v2, 6, v8
	v_and_or_b32 v3, v3, s6, v4
	v_lshl_or_b32 v0, v0, 6, v4
	v_readlane_b32 s6, v250, 2
	v_lshlrev_b32_e32 v4, 2, v8
	v_lshl_add_u32 v5, v2, 10, s86
	v_add_lshl_u32 v2, v2, s6, 10
	v_and_b32_e32 v4, 32, v4
	v_ashrrev_i32_e32 v1, 1, v8
	v_bitop3_b32 v149, v0, v2, v4 bitop3:0xde
	v_lshlrev_b32_e32 v0, 15, v12
	v_and_b32_e32 v1, -8, v1
	v_readlane_b32 s6, v250, 1
	v_and_b32_e32 v0, 0xffff0000, v0
	v_lshl_add_u32 v0, v13, 12, v0
	v_add_u32_e32 v150, s6, v1
	v_and_b32_e32 v1, 1, v12
	v_lshl_or_b32 v0, v1, 6, v0
	v_lshl_add_u32 v136, v14, 1, v0
	v_lshlrev_b32_e32 v0, 15, v9
	v_lshlrev_b32_e32 v6, 2, v148
	v_and_b32_e32 v0, 0xffff0000, v0
	v_and_b32_e32 v6, 32, v6
	s_waitcnt vmcnt(6)
	s_cmpk_lt_u32 s33, 0x100
	v_lshl_add_u32 v0, v10, 12, v0
	v_and_b32_e32 v1, 1, v9
	v_bitop3_b32 v3, v3, v5, v6 bitop3:0xde
	s_cselect_b64 s[20:21], -1, 0
	v_lshl_or_b32 v0, v1, 6, v0
	s_add_i32 s60, 0, 0x10000
	s_add_i32 s61, 0, 0x14000
	s_ashr_i32 s58, s46, 31
	s_mov_b32 s59, s46
	v_mov_b32_e32 v137, v133
	v_lshl_add_u32 v138, v11, 1, v0
	v_mov_b32_e32 v139, v133
	v_mov_b64_e32 v[140:141], 0x580
	v_mov_b64_e32 v[142:143], 0x57f
	v_add_u32_e32 v151, s60, v149
	v_add_u32_e32 v152, s61, v149
	v_add_u32_e32 v153, 0, v3
	v_mov_b32_e32 v154, 0x358637bd
	s_mov_b32 s67, 0x800000
	s_movk_i32 s69, 0x2c00
	v_lshl_add_u32 v246, s8, 8, v148
	v_ashrrev_i32_e32 v247, 31, v246
	v_lshl_add_u64 v[244:245], v[246:247], 2, s[50:51]
	global_load_dword v236, v[244:245], off
	global_load_dword v237, v[244:245], off offset:64
	global_load_dword v238, v[244:245], off offset:128
	global_load_dword v239, v[244:245], off offset:192
	global_load_dword v240, v[244:245], off offset:512
	global_load_dword v241, v[244:245], off offset:576
	global_load_dword v242, v[244:245], off offset:640
	global_load_dword v243, v[244:245], off offset:704
	s_barrier
	s_branch .LBB0_164

.LBB0_170:
	v_lshl_add_u32 v146, s8, 8, v148
	v_ashrrev_i32_e32 v147, 31, v146
	v_lshl_add_u64 v[162:163], v[146:147], 2, s[50:51]
	v_mov_b32_e32 v147, v236
	v_mov_b32_e32 v161, v237
	v_mov_b32_e32 v185, v238
	v_mov_b32_e32 v186, v239
	v_mov_b32_e32 v187, v240
	v_mov_b32_e32 v188, v241
	v_mov_b32_e32 v159, v242
	v_mov_b32_e32 v157, v243
	v_lshl_add_u32 v246, s24, 8, v148
	v_ashrrev_i32_e32 v247, 31, v246
	v_lshl_add_u64 v[244:245], v[246:247], 2, s[50:51]
	global_load_dword v236, v[244:245], off
	global_load_dword v237, v[244:245], off offset:64
	global_load_dword v238, v[244:245], off offset:128
	global_load_dword v239, v[244:245], off offset:192
	global_load_dword v240, v[244:245], off offset:512
	global_load_dword v241, v[244:245], off offset:576
	global_load_dword v242, v[244:245], off offset:640
	global_load_dword v243, v[244:245], off offset:704
	v_mov_b64_e32 v[144:145], s[56:57]
	v_lshl_add_u32 v164, s9, 7, v150
	v_or_b32_e32 v182, 16, v146
	v_or_b32_e32 v183, 32, v146
	v_or_b32_e32 v184, 48, v146
	v_add_u32_e32 v160, 0x80, v146
	v_add_u32_e32 v158, 0x90, v146
	v_add_u32_e32 v156, 0xa0, v146
	v_add_u32_e32 v155, 0xb0, v146
	v_mad_i64_i32 v[166:167], s[8:9], v146, s69, v[144:145]
	v_ashrrev_i32_e32 v165, 31, v164
	v_fmamk_f32 v146, v147, 0x3a000000, v154
	v_fmamk_f32 v147, v161, 0x3a000000, v154
	v_mul_f32_e32 v161, 0x4b800000, v146
	v_mul_f32_e32 v162, 0x4b800000, v147
	v_cmp_gt_f32_e32 vcc, s67, v146
	v_cmp_gt_f32_e64 s[8:9], s67, v147
	s_nop 0
	v_cndmask_b32_e32 v146, v146, v161, vcc
	v_cndmask_b32_e64 v147, v147, v162, s[8:9]
	v_rsq_f32_e32 v161, v146
	v_rsq_f32_e32 v168, v147
	v_lshlrev_b64 v[146:147], 1, v[164:165]
	v_lshl_add_u64 v[162:163], v[166:167], 0, v[146:147]
	v_mul_f32_e32 v164, 0x45800000, v161
	v_mul_f32_e32 v165, 0x45800000, v168
	v_cndmask_b32_e32 v164, v161, v164, vcc
	v_cndmask_b32_e64 v166, v168, v165, s[8:9]
	v_mul_f32_e32 v168, 0xbfb8aa3b, v164
	v_pk_mul_f32 v[170:171], v[126:127], v[164:165] op_sel_hi:[1,0]
	v_pk_mul_f32 v[172:173], v[124:125], v[164:165] op_sel_hi:[1,0]
	v_pk_mul_f32 v[112:113], v[112:113], v[164:165] op_sel_hi:[1,0]
	v_pk_mul_f32 v[114:115], v[114:115], v[164:165] op_sel_hi:[1,0]
	v_pk_mul_f32 v[174:175], v[122:123], v[164:165] op_sel_hi:[1,0]
	v_pk_mul_f32 v[176:177], v[120:121], v[164:165] op_sel_hi:[1,0]
	v_pk_mul_f32 v[108:109], v[108:109], v[164:165] op_sel_hi:[1,0]
	v_pk_mul_f32 v[110:111], v[110:111], v[164:165] op_sel_hi:[1,0]
	v_mul_f32_e32 v164, 0xbfb8aa3b, v166
	v_pk_mul_f32 v[180:181], v[116:117], v[166:167] op_sel_hi:[1,0]
	v_pk_mul_f32 v[126:127], v[126:127], v[168:169] op_sel_hi:[1,0]
	v_pk_mul_f32 v[124:125], v[124:125], v[168:169] op_sel_hi:[1,0]
	v_pk_mul_f32 v[116:117], v[116:117], v[164:165] op_sel_hi:[1,0]
	v_pk_mul_f32 v[178:179], v[118:119], v[166:167] op_sel_hi:[1,0]
	v_pk_mul_f32 v[122:123], v[122:123], v[168:169] op_sel_hi:[1,0]
	v_pk_mul_f32 v[120:121], v[120:121], v[168:169] op_sel_hi:[1,0]
	v_pk_mul_f32 v[118:119], v[118:119], v[164:165] op_sel_hi:[1,0]
	v_exp_f32_e32 v124, v124
	v_exp_f32_e32 v125, v125
	v_exp_f32_e32 v126, v126
	v_exp_f32_e32 v127, v127
	v_exp_f32_e32 v116, v116
	v_exp_f32_e32 v117, v117
	v_exp_f32_e32 v120, v120
	v_exp_f32_e32 v121, v121
	v_exp_f32_e32 v122, v122
	v_exp_f32_e32 v123, v123
	v_exp_f32_e32 v118, v118
	v_exp_f32_e32 v119, v119
	v_pk_add_f32 v[126:127], v[126:127], 1.0 op_sel_hi:[1,0]
	v_pk_add_f32 v[124:125], v[124:125], 1.0 op_sel_hi:[1,0]
	v_pk_add_f32 v[116:117], v[116:117], 1.0 op_sel_hi:[1,0]
	v_pk_add_f32 v[122:123], v[122:123], 1.0 op_sel_hi:[1,0]
	v_pk_add_f32 v[120:121], v[120:121], 1.0 op_sel_hi:[1,0]
	v_pk_add_f32 v[118:119], v[118:119], 1.0 op_sel_hi:[1,0]
	v_rcp_f32_e32 v124, v124
	v_rcp_f32_e32 v125, v125
	v_rcp_f32_e32 v126, v126
	v_rcp_f32_e32 v127, v127
	v_rcp_f32_e32 v116, v116
	v_rcp_f32_e32 v117, v117
	v_rcp_f32_e32 v120, v120
	v_rcp_f32_e32 v121, v121
	v_rcp_f32_e32 v122, v122
	v_rcp_f32_e32 v123, v123
	v_rcp_f32_e32 v118, v118
	v_rcp_f32_e32 v119, v119
	v_pk_mul_f32 v[104:105], v[104:105], v[166:167] op_sel_hi:[1,0]
	v_pk_mul_f32 v[124:125], v[172:173], v[124:125]
	v_pk_mul_f32 v[126:127], v[170:171], v[126:127]
	v_pk_mul_f32 v[116:117], v[180:181], v[116:117]
	v_pk_mul_f32 v[106:107], v[106:107], v[166:167] op_sel_hi:[1,0]
	v_pk_mul_f32 v[120:121], v[176:177], v[120:121]
	v_pk_mul_f32 v[122:123], v[174:175], v[122:123]
	v_pk_mul_f32 v[118:119], v[178:179], v[118:119]
	v_pk_mul_f32 v[114:115], v[114:115], v[126:127]
	v_pk_mul_f32 v[112:113], v[112:113], v[124:125]
	v_pk_mul_f32 v[116:117], v[104:105], v[116:117]
	v_cvt_pk_bf16_f32 v104, v112, v113
	v_cvt_pk_bf16_f32 v105, v114, v115
	v_pk_mul_f32 v[168:169], v[102:103], v[164:165] op_sel_hi:[1,0]
	v_pk_mul_f32 v[110:111], v[110:111], v[122:123]
	v_pk_mul_f32 v[108:109], v[108:109], v[120:121]
	v_pk_mul_f32 v[118:119], v[106:107], v[118:119]
	v_cvt_pk_bf16_f32 v106, v108, v109
	v_cvt_pk_bf16_f32 v107, v110, v111
	global_store_dwordx4 v[162:163], v[104:107], off
	v_pk_mul_f32 v[102:103], v[102:103], v[166:167] op_sel_hi:[1,0]
	v_pk_mul_f32 v[96:97], v[96:97], v[166:167] op_sel_hi:[1,0]
	v_pk_mul_f32 v[104:105], v[100:101], v[164:165] op_sel_hi:[1,0]
	v_exp_f32_e32 v106, v168
	v_exp_f32_e32 v104, v104
	v_exp_f32_e32 v107, v169
	v_exp_f32_e32 v105, v105
	v_pk_mul_f32 v[100:101], v[100:101], v[166:167] op_sel_hi:[1,0]
	v_pk_mul_f32 v[98:99], v[98:99], v[166:167] op_sel_hi:[1,0]
	v_pk_add_f32 v[106:107], v[106:107], 1.0 op_sel_hi:[1,0]
	v_pk_add_f32 v[104:105], v[104:105], 1.0 op_sel_hi:[1,0]
	v_rcp_f32_e32 v106, v106
	v_rcp_f32_e32 v104, v104
	v_rcp_f32_e32 v105, v105
	v_rcp_f32_e32 v107, v107
	v_pk_mul_f32 v[100:101], v[100:101], v[104:105]
	v_pk_mul_f32 v[102:103], v[102:103], v[106:107]
	s_nop 0
	v_pk_mul_f32 v[102:103], v[98:99], v[102:103]
	v_pk_mul_f32 v[98:99], v[96:97], v[100:101]
	v_fmamk_f32 v100, v185, 0x3a000000, v154
	v_mul_f32_e32 v101, 0x4b800000, v100
	v_cmp_gt_f32_e32 vcc, s67, v100
	v_cvt_pk_bf16_f32 v96, v116, v117
	v_cvt_pk_bf16_f32 v97, v118, v119
	v_cvt_pk_bf16_f32 v98, v98, v99
	v_cvt_pk_bf16_f32 v99, v102, v103
	s_nop 1
	v_cndmask_b32_e32 v100, v100, v101, vcc
	v_rsq_f32_e32 v102, v100
	v_mad_i64_i32 v[100:101], s[8:9], v182, s69, v[144:145]
	v_lshl_add_u64 v[100:101], v[100:101], 0, v[146:147]
	global_store_dwordx4 v[100:101], v[96:99], off
	s_nop 1
	v_mul_f32_e32 v96, 0x45800000, v102
	v_cndmask_b32_e32 v96, v102, v96, vcc
	v_mul_f32_e32 v98, 0xbfb8aa3b, v96
	v_pk_mul_f32 v[100:101], v[94:95], v[98:99] op_sel_hi:[1,0]
	v_pk_mul_f32 v[102:103], v[92:93], v[98:99] op_sel_hi:[1,0]
	v_exp_f32_e32 v100, v100
	v_exp_f32_e32 v102, v102
	v_exp_f32_e32 v101, v101
	v_exp_f32_e32 v103, v103
	v_pk_mul_f32 v[94:95], v[94:95], v[96:97] op_sel_hi:[1,0]
	v_pk_mul_f32 v[92:93], v[92:93], v[96:97] op_sel_hi:[1,0]
	v_pk_add_f32 v[100:101], v[100:101], 1.0 op_sel_hi:[1,0]
	v_pk_add_f32 v[102:103], v[102:103], 1.0 op_sel_hi:[1,0]
	v_rcp_f32_e32 v100, v100
	v_rcp_f32_e32 v102, v102
	v_rcp_f32_e32 v103, v103
	v_rcp_f32_e32 v101, v101
	v_pk_mul_f32 v[88:89], v[88:89], v[96:97] op_sel_hi:[1,0]
	v_pk_mul_f32 v[90:91], v[90:91], v[96:97] op_sel_hi:[1,0]
	v_pk_mul_f32 v[92:93], v[92:93], v[102:103]
	v_pk_mul_f32 v[94:95], v[94:95], v[100:101]
	v_pk_mul_f32 v[88:89], v[88:89], v[92:93]
	v_pk_mul_f32 v[90:91], v[90:91], v[94:95]
	v_pk_mul_f32 v[92:93], v[86:87], v[98:99] op_sel_hi:[1,0]
	v_pk_mul_f32 v[94:95], v[84:85], v[98:99] op_sel_hi:[1,0]
	v_exp_f32_e32 v92, v92
	v_exp_f32_e32 v94, v94
	v_exp_f32_e32 v93, v93
	v_exp_f32_e32 v95, v95
	v_pk_mul_f32 v[86:87], v[86:87], v[96:97] op_sel_hi:[1,0]
	v_pk_mul_f32 v[84:85], v[84:85], v[96:97] op_sel_hi:[1,0]
	v_pk_add_f32 v[92:93], v[92:93], 1.0 op_sel_hi:[1,0]
	v_pk_add_f32 v[94:95], v[94:95], 1.0 op_sel_hi:[1,0]
	v_rcp_f32_e32 v92, v92
	v_rcp_f32_e32 v94, v94
	v_rcp_f32_e32 v95, v95
	v_rcp_f32_e32 v93, v93
	v_pk_mul_f32 v[80:81], v[80:81], v[96:97] op_sel_hi:[1,0]
	v_pk_mul_f32 v[82:83], v[82:83], v[96:97] op_sel_hi:[1,0]
	v_pk_mul_f32 v[84:85], v[84:85], v[94:95]
	v_pk_mul_f32 v[86:87], v[86:87], v[92:93]
	s_nop 0
	v_pk_mul_f32 v[86:87], v[82:83], v[86:87]
	v_pk_mul_f32 v[82:83], v[80:81], v[84:85]
	v_fmamk_f32 v84, v186, 0x3a000000, v154
	v_mul_f32_e32 v85, 0x4b800000, v84
	v_cmp_gt_f32_e32 vcc, s67, v84
	v_cvt_pk_bf16_f32 v80, v88, v89
	v_cvt_pk_bf16_f32 v81, v90, v91
	v_cvt_pk_bf16_f32 v82, v82, v83
	v_cvt_pk_bf16_f32 v83, v86, v87
	s_nop 1
	v_cndmask_b32_e32 v84, v84, v85, vcc
	v_rsq_f32_e32 v86, v84
	v_mad_i64_i32 v[84:85], s[8:9], v183, s69, v[144:145]
	v_lshl_add_u64 v[84:85], v[84:85], 0, v[146:147]
	global_store_dwordx4 v[84:85], v[80:83], off
	s_nop 1
	v_mul_f32_e32 v80, 0x45800000, v86
	v_cndmask_b32_e32 v80, v86, v80, vcc
	v_mul_f32_e32 v82, 0xbfb8aa3b, v80
	v_pk_mul_f32 v[84:85], v[78:79], v[82:83] op_sel_hi:[1,0]
	v_pk_mul_f32 v[86:87], v[76:77], v[82:83] op_sel_hi:[1,0]
	v_exp_f32_e32 v84, v84
	v_exp_f32_e32 v86, v86
	v_exp_f32_e32 v85, v85
	v_exp_f32_e32 v87, v87
	v_pk_mul_f32 v[78:79], v[78:79], v[80:81] op_sel_hi:[1,0]
	v_pk_mul_f32 v[76:77], v[76:77], v[80:81] op_sel_hi:[1,0]
	v_pk_add_f32 v[84:85], v[84:85], 1.0 op_sel_hi:[1,0]
	v_pk_add_f32 v[86:87], v[86:87], 1.0 op_sel_hi:[1,0]
	v_rcp_f32_e32 v84, v84
	v_rcp_f32_e32 v86, v86
	v_rcp_f32_e32 v87, v87
	v_rcp_f32_e32 v85, v85
	v_pk_mul_f32 v[72:73], v[72:73], v[80:81] op_sel_hi:[1,0]
	v_pk_mul_f32 v[74:75], v[74:75], v[80:81] op_sel_hi:[1,0]
	v_pk_mul_f32 v[76:77], v[76:77], v[86:87]
	v_pk_mul_f32 v[78:79], v[78:79], v[84:85]
	v_pk_mul_f32 v[72:73], v[72:73], v[76:77]
	v_pk_mul_f32 v[74:75], v[74:75], v[78:79]
	v_pk_mul_f32 v[76:77], v[70:71], v[82:83] op_sel_hi:[1,0]
	v_pk_mul_f32 v[78:79], v[68:69], v[82:83] op_sel_hi:[1,0]
	v_exp_f32_e32 v76, v76
	v_exp_f32_e32 v78, v78
	v_exp_f32_e32 v77, v77
	v_exp_f32_e32 v79, v79
	v_pk_mul_f32 v[70:71], v[70:71], v[80:81] op_sel_hi:[1,0]
	v_pk_mul_f32 v[68:69], v[68:69], v[80:81] op_sel_hi:[1,0]
	v_pk_add_f32 v[76:77], v[76:77], 1.0 op_sel_hi:[1,0]
	v_pk_add_f32 v[78:79], v[78:79], 1.0 op_sel_hi:[1,0]
	v_rcp_f32_e32 v76, v76
	v_rcp_f32_e32 v78, v78
	v_rcp_f32_e32 v79, v79
	v_rcp_f32_e32 v77, v77
	v_pk_mul_f32 v[64:65], v[64:65], v[80:81] op_sel_hi:[1,0]
	v_pk_mul_f32 v[66:67], v[66:67], v[80:81] op_sel_hi:[1,0]
	v_pk_mul_f32 v[68:69], v[68:69], v[78:79]
	v_pk_mul_f32 v[70:71], v[70:71], v[76:77]
	s_nop 0
	v_pk_mul_f32 v[70:71], v[66:67], v[70:71]
	v_pk_mul_f32 v[66:67], v[64:65], v[68:69]
	v_fmamk_f32 v68, v187, 0x3a000000, v154
	v_mul_f32_e32 v69, 0x4b800000, v68
	v_cmp_gt_f32_e32 vcc, s67, v68
	v_cvt_pk_bf16_f32 v64, v72, v73
	v_cvt_pk_bf16_f32 v65, v74, v75
	v_cvt_pk_bf16_f32 v66, v66, v67
	v_cvt_pk_bf16_f32 v67, v70, v71
	s_nop 1
	v_cndmask_b32_e32 v68, v68, v69, vcc
	v_rsq_f32_e32 v70, v68
	v_mad_i64_i32 v[68:69], s[8:9], v184, s69, v[144:145]
	v_lshl_add_u64 v[68:69], v[68:69], 0, v[146:147]
	global_store_dwordx4 v[68:69], v[64:67], off
	s_nop 1
	v_mul_f32_e32 v64, 0x45800000, v70
	v_cndmask_b32_e32 v64, v70, v64, vcc
	v_mul_f32_e32 v66, 0xbfb8aa3b, v64
	v_pk_mul_f32 v[68:69], v[62:63], v[66:67] op_sel_hi:[1,0]
	v_pk_mul_f32 v[70:71], v[60:61], v[66:67] op_sel_hi:[1,0]
	v_exp_f32_e32 v68, v68
	v_exp_f32_e32 v70, v70
	v_exp_f32_e32 v69, v69
	v_exp_f32_e32 v71, v71
	v_pk_mul_f32 v[62:63], v[62:63], v[64:65] op_sel_hi:[1,0]
	v_pk_mul_f32 v[60:61], v[60:61], v[64:65] op_sel_hi:[1,0]
	v_pk_add_f32 v[68:69], v[68:69], 1.0 op_sel_hi:[1,0]
	v_pk_add_f32 v[70:71], v[70:71], 1.0 op_sel_hi:[1,0]
	v_rcp_f32_e32 v68, v68
	v_rcp_f32_e32 v70, v70
	v_rcp_f32_e32 v71, v71
	v_rcp_f32_e32 v69, v69
	v_pk_mul_f32 v[56:57], v[56:57], v[64:65] op_sel_hi:[1,0]
	v_pk_mul_f32 v[58:59], v[58:59], v[64:65] op_sel_hi:[1,0]
	v_pk_mul_f32 v[60:61], v[60:61], v[70:71]
	v_pk_mul_f32 v[62:63], v[62:63], v[68:69]
	v_pk_mul_f32 v[56:57], v[56:57], v[60:61]
	v_pk_mul_f32 v[58:59], v[58:59], v[62:63]
	v_pk_mul_f32 v[60:61], v[54:55], v[66:67] op_sel_hi:[1,0]
	v_pk_mul_f32 v[62:63], v[52:53], v[66:67] op_sel_hi:[1,0]
	v_exp_f32_e32 v60, v60
	v_exp_f32_e32 v62, v62
	v_exp_f32_e32 v61, v61
	v_exp_f32_e32 v63, v63
	v_pk_mul_f32 v[54:55], v[54:55], v[64:65] op_sel_hi:[1,0]
	v_pk_mul_f32 v[52:53], v[52:53], v[64:65] op_sel_hi:[1,0]
	v_pk_add_f32 v[60:61], v[60:61], 1.0 op_sel_hi:[1,0]
	v_pk_add_f32 v[62:63], v[62:63], 1.0 op_sel_hi:[1,0]
	v_rcp_f32_e32 v60, v60
	v_rcp_f32_e32 v62, v62
	v_rcp_f32_e32 v63, v63
	v_rcp_f32_e32 v61, v61
	v_pk_mul_f32 v[48:49], v[48:49], v[64:65] op_sel_hi:[1,0]
	v_pk_mul_f32 v[50:51], v[50:51], v[64:65] op_sel_hi:[1,0]
	v_pk_mul_f32 v[52:53], v[52:53], v[62:63]
	v_pk_mul_f32 v[54:55], v[54:55], v[60:61]
	s_nop 0
	v_pk_mul_f32 v[54:55], v[50:51], v[54:55]
	v_pk_mul_f32 v[50:51], v[48:49], v[52:53]
	v_fmamk_f32 v52, v188, 0x3a000000, v154
	v_mul_f32_e32 v53, 0x4b800000, v52
	v_cmp_gt_f32_e32 vcc, s67, v52
	v_cvt_pk_bf16_f32 v48, v56, v57
	v_cvt_pk_bf16_f32 v49, v58, v59
	v_cvt_pk_bf16_f32 v50, v50, v51
	v_cvt_pk_bf16_f32 v51, v54, v55
	s_nop 1
	v_cndmask_b32_e32 v52, v52, v53, vcc
	v_rsq_f32_e32 v54, v52
	v_mad_i64_i32 v[52:53], s[8:9], v160, s69, v[144:145]
	v_lshl_add_u64 v[52:53], v[52:53], 0, v[146:147]
	global_store_dwordx4 v[52:53], v[48:51], off
	s_nop 1
	v_mul_f32_e32 v48, 0x45800000, v54
	v_cndmask_b32_e32 v48, v54, v48, vcc
	v_mul_f32_e32 v50, 0xbfb8aa3b, v48
	v_pk_mul_f32 v[52:53], v[46:47], v[50:51] op_sel_hi:[1,0]
	v_pk_mul_f32 v[54:55], v[44:45], v[50:51] op_sel_hi:[1,0]
	v_exp_f32_e32 v52, v52
	v_exp_f32_e32 v54, v54
	v_exp_f32_e32 v53, v53
	v_exp_f32_e32 v55, v55
	v_pk_mul_f32 v[46:47], v[46:47], v[48:49] op_sel_hi:[1,0]
	v_pk_mul_f32 v[44:45], v[44:45], v[48:49] op_sel_hi:[1,0]
	v_pk_add_f32 v[52:53], v[52:53], 1.0 op_sel_hi:[1,0]
	v_pk_add_f32 v[54:55], v[54:55], 1.0 op_sel_hi:[1,0]
	v_rcp_f32_e32 v52, v52
	v_rcp_f32_e32 v54, v54
	v_rcp_f32_e32 v55, v55
	v_rcp_f32_e32 v53, v53
	v_pk_mul_f32 v[40:41], v[40:41], v[48:49] op_sel_hi:[1,0]
	v_pk_mul_f32 v[42:43], v[42:43], v[48:49] op_sel_hi:[1,0]
	v_pk_mul_f32 v[44:45], v[44:45], v[54:55]
	v_pk_mul_f32 v[46:47], v[46:47], v[52:53]
	v_pk_mul_f32 v[40:41], v[40:41], v[44:45]
	v_pk_mul_f32 v[42:43], v[42:43], v[46:47]
	v_pk_mul_f32 v[44:45], v[38:39], v[50:51] op_sel_hi:[1,0]
	v_pk_mul_f32 v[46:47], v[36:37], v[50:51] op_sel_hi:[1,0]
	v_exp_f32_e32 v44, v44
	v_exp_f32_e32 v46, v46
	v_exp_f32_e32 v45, v45
	v_exp_f32_e32 v47, v47
	v_pk_mul_f32 v[38:39], v[38:39], v[48:49] op_sel_hi:[1,0]
	v_pk_mul_f32 v[36:37], v[36:37], v[48:49] op_sel_hi:[1,0]
	v_pk_add_f32 v[44:45], v[44:45], 1.0 op_sel_hi:[1,0]
	v_pk_add_f32 v[46:47], v[46:47], 1.0 op_sel_hi:[1,0]
	v_rcp_f32_e32 v44, v44
	v_rcp_f32_e32 v46, v46
	v_rcp_f32_e32 v47, v47
	v_rcp_f32_e32 v45, v45
	v_pk_mul_f32 v[32:33], v[32:33], v[48:49] op_sel_hi:[1,0]
	v_pk_mul_f32 v[34:35], v[34:35], v[48:49] op_sel_hi:[1,0]
	v_pk_mul_f32 v[36:37], v[36:37], v[46:47]
	v_pk_mul_f32 v[38:39], v[38:39], v[44:45]
	s_nop 0
	v_pk_mul_f32 v[38:39], v[34:35], v[38:39]
	v_pk_mul_f32 v[34:35], v[32:33], v[36:37]
	v_fmamk_f32 v36, v159, 0x3a000000, v154
	v_mul_f32_e32 v37, 0x4b800000, v36
	v_cmp_gt_f32_e32 vcc, s67, v36
	v_cvt_pk_bf16_f32 v32, v40, v41
	v_cvt_pk_bf16_f32 v33, v42, v43
	v_cvt_pk_bf16_f32 v34, v34, v35
	v_cvt_pk_bf16_f32 v35, v38, v39
	s_nop 1
	v_cndmask_b32_e32 v36, v36, v37, vcc
	v_rsq_f32_e32 v38, v36
	v_mad_i64_i32 v[36:37], s[8:9], v158, s69, v[144:145]
	v_lshl_add_u64 v[36:37], v[36:37], 0, v[146:147]
	global_store_dwordx4 v[36:37], v[32:35], off
	s_nop 1
	v_mul_f32_e32 v32, 0x45800000, v38
	v_cndmask_b32_e32 v32, v38, v32, vcc
	v_mul_f32_e32 v34, 0xbfb8aa3b, v32
	v_pk_mul_f32 v[36:37], v[30:31], v[34:35] op_sel_hi:[1,0]
	v_pk_mul_f32 v[38:39], v[28:29], v[34:35] op_sel_hi:[1,0]
	v_exp_f32_e32 v36, v36
	v_exp_f32_e32 v38, v38
	v_exp_f32_e32 v37, v37
	v_exp_f32_e32 v39, v39
	v_pk_mul_f32 v[30:31], v[30:31], v[32:33] op_sel_hi:[1,0]
	v_pk_mul_f32 v[28:29], v[28:29], v[32:33] op_sel_hi:[1,0]
	v_pk_add_f32 v[36:37], v[36:37], 1.0 op_sel_hi:[1,0]
	v_pk_add_f32 v[38:39], v[38:39], 1.0 op_sel_hi:[1,0]
	v_rcp_f32_e32 v36, v36
	v_rcp_f32_e32 v38, v38
	v_rcp_f32_e32 v39, v39
	v_rcp_f32_e32 v37, v37
	v_pk_mul_f32 v[24:25], v[24:25], v[32:33] op_sel_hi:[1,0]
	v_pk_mul_f32 v[26:27], v[26:27], v[32:33] op_sel_hi:[1,0]
	v_pk_mul_f32 v[28:29], v[28:29], v[38:39]
	v_pk_mul_f32 v[30:31], v[30:31], v[36:37]
	v_pk_mul_f32 v[24:25], v[24:25], v[28:29]
	v_pk_mul_f32 v[26:27], v[26:27], v[30:31]
	v_pk_mul_f32 v[28:29], v[22:23], v[34:35] op_sel_hi:[1,0]
	v_pk_mul_f32 v[30:31], v[20:21], v[34:35] op_sel_hi:[1,0]
	v_exp_f32_e32 v28, v28
	v_exp_f32_e32 v30, v30
	v_exp_f32_e32 v29, v29
	v_exp_f32_e32 v31, v31
	v_pk_mul_f32 v[22:23], v[22:23], v[32:33] op_sel_hi:[1,0]
	v_pk_mul_f32 v[20:21], v[20:21], v[32:33] op_sel_hi:[1,0]
	v_pk_add_f32 v[28:29], v[28:29], 1.0 op_sel_hi:[1,0]
	v_pk_add_f32 v[30:31], v[30:31], 1.0 op_sel_hi:[1,0]
	v_rcp_f32_e32 v28, v28
	v_rcp_f32_e32 v30, v30
	v_rcp_f32_e32 v31, v31
	v_rcp_f32_e32 v29, v29
	v_pk_mul_f32 v[16:17], v[16:17], v[32:33] op_sel_hi:[1,0]
	v_pk_mul_f32 v[18:19], v[18:19], v[32:33] op_sel_hi:[1,0]
	v_pk_mul_f32 v[20:21], v[20:21], v[30:31]
	v_pk_mul_f32 v[22:23], v[22:23], v[28:29]
	s_nop 0
	v_pk_mul_f32 v[22:23], v[18:19], v[22:23]
	v_pk_mul_f32 v[18:19], v[16:17], v[20:21]
	v_fmamk_f32 v20, v157, 0x3a000000, v154
	v_mul_f32_e32 v21, 0x4b800000, v20
	v_cmp_gt_f32_e32 vcc, s67, v20
	v_cvt_pk_bf16_f32 v16, v24, v25
	v_cvt_pk_bf16_f32 v17, v26, v27
	v_cvt_pk_bf16_f32 v18, v18, v19
	v_cvt_pk_bf16_f32 v19, v22, v23
	s_nop 1
	v_cndmask_b32_e32 v20, v20, v21, vcc
	v_rsq_f32_e32 v22, v20
	v_mad_i64_i32 v[20:21], s[8:9], v156, s69, v[144:145]
	v_lshl_add_u64 v[20:21], v[20:21], 0, v[146:147]
	global_store_dwordx4 v[20:21], v[16:19], off
	s_nop 1
	v_mul_f32_e32 v16, 0x45800000, v22
	v_cndmask_b32_e32 v16, v22, v16, vcc
	v_mul_f32_e32 v18, 0xbfb8aa3b, v16
	v_pk_mul_f32 v[20:21], v[14:15], v[18:19] op_sel_hi:[1,0]
	v_pk_mul_f32 v[22:23], v[12:13], v[18:19] op_sel_hi:[1,0]
	v_exp_f32_e32 v20, v20
	v_exp_f32_e32 v22, v22
	v_exp_f32_e32 v21, v21
	v_exp_f32_e32 v23, v23
	v_pk_mul_f32 v[14:15], v[14:15], v[16:17] op_sel_hi:[1,0]
	v_pk_mul_f32 v[12:13], v[12:13], v[16:17] op_sel_hi:[1,0]
	v_pk_add_f32 v[20:21], v[20:21], 1.0 op_sel_hi:[1,0]
	v_pk_add_f32 v[22:23], v[22:23], 1.0 op_sel_hi:[1,0]
	v_rcp_f32_e32 v20, v20
	v_rcp_f32_e32 v22, v22
	v_rcp_f32_e32 v23, v23
	v_rcp_f32_e32 v21, v21
	v_pk_mul_f32 v[8:9], v[8:9], v[16:17] op_sel_hi:[1,0]
	v_pk_mul_f32 v[10:11], v[10:11], v[16:17] op_sel_hi:[1,0]
	v_pk_mul_f32 v[12:13], v[12:13], v[22:23]
	v_pk_mul_f32 v[14:15], v[14:15], v[20:21]
	v_pk_mul_f32 v[8:9], v[8:9], v[12:13]
	v_pk_mul_f32 v[10:11], v[10:11], v[14:15]
	v_pk_mul_f32 v[12:13], v[6:7], v[18:19] op_sel_hi:[1,0]
	v_pk_mul_f32 v[14:15], v[4:5], v[18:19] op_sel_hi:[1,0]
	v_exp_f32_e32 v12, v12
	v_exp_f32_e32 v14, v14
	v_exp_f32_e32 v13, v13
	v_exp_f32_e32 v15, v15
	v_pk_mul_f32 v[6:7], v[6:7], v[16:17] op_sel_hi:[1,0]
	v_pk_mul_f32 v[4:5], v[4:5], v[16:17] op_sel_hi:[1,0]
	v_pk_add_f32 v[12:13], v[12:13], 1.0 op_sel_hi:[1,0]
	v_pk_add_f32 v[14:15], v[14:15], 1.0 op_sel_hi:[1,0]
	v_rcp_f32_e32 v12, v12
	v_rcp_f32_e32 v14, v14
	v_rcp_f32_e32 v15, v15
	v_rcp_f32_e32 v13, v13
	v_pk_mul_f32 v[0:1], v[0:1], v[16:17] op_sel_hi:[1,0]
	v_pk_mul_f32 v[2:3], v[2:3], v[16:17] op_sel_hi:[1,0]
	v_pk_mul_f32 v[4:5], v[4:5], v[14:15]
	v_pk_mul_f32 v[6:7], v[6:7], v[12:13]
	s_andn2_b64 vcc, exec, s[6:7]
	v_pk_mul_f32 v[6:7], v[2:3], v[6:7]
	v_pk_mul_f32 v[2:3], v[0:1], v[4:5]
	v_mad_i64_i32 v[4:5], s[8:9], v155, s69, v[144:145]
	v_lshl_add_u64 v[4:5], v[4:5], 0, v[146:147]
	s_mov_b64 s[6:7], -1
	v_cvt_pk_bf16_f32 v0, v8, v9
	v_cvt_pk_bf16_f32 v1, v10, v11
	v_cvt_pk_bf16_f32 v2, v2, v3
	v_cvt_pk_bf16_f32 v3, v6, v7
	global_store_dwordx4 v[4:5], v[0:3], off
	s_cbranch_vccnz .LBB0_163
	s_andn2_b64 vcc, exec, s[16:17]
	s_cbranch_vccnz .LBB0_162
	s_barrier
	s_branch .LBB0_162
